# speedup vs baseline: 1.0114x; 1.0114x over previous
; #define LAS __attribute__((address_space(3)))
; #define PG8_STAGE(bufoff, gbase, voff) do { _Pragma("unroll") for (int _i = 0; _i < 2; ++_i) \
;         __builtin_amdgcn_global_load_lds((const unsigned*)((const char*)(gbase) + (voff)[_i]), (LAS unsigned*)(lds + (bufoff) + ldsw + _i * 8192), 16, 0, 0); } while (0)
;     __device__ __forceinline__ u32x2 pre(int, int, int) const { return (u32x2){0u, 0u}; }
;     __device__ __forceinline__ u32x2 pre(int, int, int) const { return (u32x2){0u, 0u}; }
; template <class Epi, class Sched, bool HN = false>
; __device__ __forceinline__ void gemm_phase(LAS unsigned char* lds, const Gemm g, const Sched& S, const Epi& E) {
;     ...
;     PG8_STAGE(PG8_SB(0, 0), cB, voffB); if constexpr (!HN) PG8_STAGE(PG8_SB(0, 1), cB + hstep, voffB); PG8_STAGE(PG8_SA(0, 0), cA, voffA); PG8_STAGE(PG8_SA(0, 1), cA + hstep, voffA);
;     __device__ __forceinline__ void pre(const Unit& un, int wr, int wid, int lane, LAS unsigned char*) const {
;         LAS float* tab = (LAS float*)(ldsb + 131072) + wid * 256;
; #pragma unroll
;         for (int a = 0; a < 2; ++a) {
;             const size_t row = (size_t)(un.pm * 256 + wr * 64 + 128 * a + lane);
;             const f32x4* pa = (const f32x4*)(ssqa + row * 16); const f32x4* ps = (const f32x4*)(ssqs + row * 32);
;             float sa = 0.f, ss = 0.f;
; #pragma unroll
;             for (int i = 0; i < 4; ++i) { const f32x4 t = pa[i]; sa += (t[0] + t[1]) + (t[2] + t[3]); }
; #pragma unroll
;             for (int i = 0; i < 8; ++i) { const f32x4 u = ps[i]; ss += (u[0] + u[1]) + (u[2] + u[3]); }
;             const float ra = rsqrtf(sa * (1.f / 1024.f) + 1e-6f), rs = rsqrtf(ss * (1.f / 1024.f) + 1e-6f);
;             tab[(a * 64 + lane) * 2] = ra / rs; tab[(a * 64 + lane) * 2 + 1] = rs;
.LBB0_1150:
	s_add_u32 s24, s92, s20
	s_addc_u32 s25, s93, s21
	s_add_u32 s20, s24, s88
	s_addc_u32 s21, s25, 0
	s_add_u32 s22, s24, 0x1dd1b000
	s_addc_u32 s23, s25, 0
	s_add_u32 s67, s20, 0xc00000
	s_addc_u32 s70, s21, 0
	s_add_u32 s20, s24, 0x19000000
	s_addc_u32 s21, s25, 0
	s_andn2_b64 vcc, exec, s[0:1]
	s_cbranch_vccnz .LBB0_1188
	v_ashrrev_i32_e32 v1, 31, v37
	v_lshrrev_b32_e32 v1, 26, v1
	v_add_u32_e32 v1, v37, v1
	v_ashrrev_i32_e32 v24, 6, v1
	v_bfe_i32 v1, v37, 27, 1
	v_lshlrev_b32_e32 v0, 4, v37
	v_lshrrev_b32_e32 v1, 22, v1
	v_add_u32_e32 v1, v0, v1
	v_and_b32_e32 v1, 0xfffffc00, v1
	v_sub_u32_e32 v1, v0, v1
	v_lshrrev_b32_e32 v2, 4, v1
	v_bitop3_b32 v1, v2, v1, 32 bitop3:0x6c
	v_ashrrev_i32_e32 v3, 31, v1
	v_lshrrev_b32_e32 v3, 26, v3
	v_add_u32_e32 v3, v1, v3
	v_lshlrev_b32_e32 v2, 3, v24
	v_ashrrev_i32_e32 v35, 6, v3
	v_and_b32_e32 v3, 0xc0, v3
	v_and_b32_e32 v2, -16, v2
	v_sub_u32_e32 v1, v1, v3
	v_add_u32_e32 v2, v35, v2
	v_ashrrev_i16_sdwa v1, v252, sext(v1) dst_sel:DWORD dst_unused:UNUSED_PAD src0_sel:DWORD src1_sel:BYTE_0
	v_lshlrev_b32_e32 v4, 5, v24
	v_bfe_i32 v36, v1, 0, 16
	v_lshlrev_b32_e32 v1, 1, v2
	v_lshrrev_b32_e32 v3, 2, v2
	v_and_b32_e32 v5, 3, v35
	s_mov_b32 s0, 0xfffe0
	v_and_b32_e32 v4, 32, v4
	v_and_b32_e32 v1, 24, v1
	v_and_b32_e32 v3, 4, v3
	v_and_or_b32 v5, v2, s0, v5
	v_or3_b32 v1, v5, v3, v1
	v_add_lshl_u32 v3, v4, v36, 1
	v_add_u32_e32 v0, 0x2000, v0
	v_lshl_add_u32 v134, v1, 12, v3
	v_ashrrev_i32_e32 v1, 31, v0
	v_lshrrev_b32_e32 v1, 22, v1
	v_add_u32_e32 v1, v0, v1
	v_ashrrev_i32_e32 v38, 10, v1
	v_mul_i32_i24_e32 v1, 0x400, v38
	v_sub_u32_e32 v0, v0, v1
	v_lshrrev_b32_e32 v1, 4, v0
	v_bitop3_b32 v0, v1, v0, 32 bitop3:0x6c
	v_lshl_add_u32 v132, v2, 12, v3
	v_ashrrev_i32_e32 v2, 31, v0
	s_add_u32 s34, s24, 0x1b310000
	v_lshrrev_b32_e32 v2, 26, v2
	v_writelane_b32 v254, s42, 47
	s_addc_u32 s35, s25, 0
	v_lshlrev_b32_e32 v1, 3, v38
	v_add_u32_e32 v2, v0, v2
	v_writelane_b32 v254, s43, 48
	s_add_u32 s42, s24, 0x1b208000
	v_and_b32_e32 v1, -16, v1
	v_ashrrev_i32_e32 v39, 6, v2
	s_addc_u32 s43, s25, 0
	s_ashr_i32 s31, s30, 6
	v_add_u32_e32 v1, v39, v1
	v_and_b32_e32 v2, 0xc0, v2
	v_and_b32_e32 v4, 3, v39
	s_ashr_i32 s38, s30, 8
	s_ashr_i32 s61, s60, 31
	s_ashr_i32 s59, s58, 31
	v_sub_u32_e32 v0, v0, v2
	v_and_or_b32 v4, v1, s0, v4
	s_lshl_b32 s71, s31, 10
	s_lshl_b32 s39, s38, 6
	s_lshl_b64 s[36:37], s[60:61], 20
	s_lshl_b64 s[0:1], s[58:59], 20
	v_ashrrev_i16_sdwa v0, v252, sext(v0) dst_sel:DWORD dst_unused:UNUSED_PAD src0_sel:DWORD src1_sel:BYTE_0
	s_add_u32 s62, s67, s0
	v_lshlrev_b32_e32 v3, 5, v38
	v_bfe_i32 v40, v0, 0, 16
	v_lshlrev_b32_e32 v0, 1, v1
	v_lshrrev_b32_e32 v2, 2, v1
	s_addc_u32 s63, s70, s1
	s_lshl_b32 s0, s60, 8
	v_and_b32_e32 v34, 63, v37
	v_and_b32_e32 v3, 32, v3
	v_and_b32_e32 v0, 24, v0
	v_and_b32_e32 v2, 4, v2
	s_add_i32 s0, s0, s39
	v_or3_b32 v0, v4, v2, v0
	v_add_lshl_u32 v2, v3, v40, 1
	s_add_i32 s59, s71, 0
	v_or_b32_e32 v4, s0, v34
	v_lshl_add_u32 v138, v0, 12, v2
	s_add_i32 s61, s59, 0x20000
	v_lshlrev_b32_e32 v0, 3, v34
	v_ashrrev_i32_e32 v5, 31, v4
	v_lshl_add_u32 v136, v1, 12, v2
	v_add_u32_e32 v148, s61, v0
	v_lshlrev_b64 v[0:1], 6, v[4:5]
	v_lshl_add_u64 v[6:7], s[34:35], 0, v[0:1]
	global_load_dwordx4 v[0:3], v[6:7], off offset:48
	global_load_dwordx4 v[8:11], v[6:7], off offset:32
	global_load_dwordx4 v[12:15], v[6:7], off offset:16
	global_load_dwordx4 v[16:19], v[6:7], off
	v_lshlrev_b64 v[20:21], 7, v[4:5]
	v_lshl_add_u64 v[30:31], s[42:43], 0, v[20:21]
	global_load_dwordx4 v[50:53], v[30:31], off offset:48
	global_load_dwordx4 v[54:57], v[30:31], off offset:32
	global_load_dwordx4 v[58:61], v[30:31], off
	global_load_dwordx4 v[62:65], v[30:31], off offset:16
	global_load_dwordx4 v[66:69], v[30:31], off offset:112
	global_load_dwordx4 v[70:73], v[30:31], off offset:96
	global_load_dwordx4 v[74:77], v[30:31], off offset:80
	global_load_dwordx4 v[78:81], v[30:31], off offset:64
	s_mov_b32 s0, 0x358637bd
	s_mov_b32 s2, 0x3a800000
	s_add_i32 m0, s59, 0x10000
	v_mov_b32_e32 v135, v25
	v_mov_b32_e32 v139, v25
	v_mov_b32_e32 v133, v25
	v_mov_b32_e32 v137, v25
	s_waitcnt vmcnt(2)
	v_add_f32_e32 v8, v8, v9
	v_add_f32_e32 v10, v10, v11
	s_waitcnt vmcnt(0)
	v_mov_b32_e32 v6, v17
	v_mov_b32_e32 v7, v18
	v_mov_b32_e32 v17, v19
	v_pk_add_f32 v[6:7], v[6:7], v[16:17]
	v_mov_b32_e32 v9, v2
	v_add_f32_e32 v5, v6, v7
	v_mov_b32_e32 v6, v13
	v_mov_b32_e32 v7, v14
	v_mov_b32_e32 v13, v15
	v_pk_add_f32 v[6:7], v[6:7], v[12:13]
	v_pk_add_f32 v[6:7], v[6:7], v[6:7] op_sel:[0,1] op_sel_hi:[1,0]
	v_mov_b32_e32 v11, v3
	v_pk_add_f32 v[2:3], v[8:9], v[10:11]
	s_waitcnt vmcnt(3)
	v_add_f32_e32 v44, v50, v51
	v_add_f32_e32 v46, v52, v53
	s_waitcnt vmcnt(1)
	v_mov_b32_e32 v32, v58
	s_waitcnt vmcnt(0)
	v_mov_b32_e32 v33, v62
	v_mov_b32_e32 v26, v59
	v_mov_b32_e32 v27, v63
	v_pk_add_f32 v[20:21], v[32:33], v[26:27]
	v_mov_b32_e32 v26, v60
	v_mov_b32_e32 v27, v64
	v_mov_b32_e32 v28, v61
	v_mov_b32_e32 v29, v65
	v_pk_add_f32 v[22:23], v[26:27], v[28:29]
	s_nop 0
	v_pk_add_f32 v[20:21], v[20:21], v[22:23]
	s_nop 0
	v_add_f32_e32 v7, 0, v20
	v_add_f32_e32 v32, v7, v21
	v_mov_b32_e32 v20, v55
	v_mov_b32_e32 v21, v56
	v_mov_b32_e32 v17, v57
	v_mov_b32_e32 v16, v54
	v_pk_add_f32 v[16:17], v[20:21], v[16:17]
	v_mov_b32_e32 v7, v1
	v_pk_add_f32 v[42:43], v[16:17], v[16:17] op_sel:[0,1] op_sel_hi:[1,0]
	s_waitcnt vmcnt(2)
	v_add_f32_e32 v16, v70, v71
	v_add_f32_e32 v18, v72, v73
	s_waitcnt vmcnt(0)
; #define PG8_STAGE(bufoff, gbase, voff) do { _Pragma("unroll") for (int _i = 0; _i < 2; ++_i) \
;         __builtin_amdgcn_global_load_lds((const unsigned*)((const char*)(gbase) + (voff)[_i]), (LAS unsigned*)(lds + (bufoff) + ldsw + _i * 8192), 16, 0, 0); } while (0)
; #define PG8_WAIT_V(n) asm volatile("s_waitcnt vmcnt(" #n ")" ::: "memory")
; #define PG8_BAR __builtin_amdgcn_s_barrier()
; template <class Epi, class Sched, bool HN = false>
; __device__ __forceinline__ void gemm_phase(LAS unsigned char* lds, const Gemm g, const Sched& S, const Epi& E) {
;     ...
;     PG8_STAGE(PG8_SB(0, 0), cB, voffB); if constexpr (!HN) PG8_STAGE(PG8_SB(0, 1), cB + hstep, voffB); PG8_STAGE(PG8_SA(0, 0), cA, voffA); PG8_STAGE(PG8_SA(0, 1), cA + hstep, voffA);
;     if (wr == 1) PG8_BAR;
;     PG8_WAIT_V(2); PG8_BAR;
;     PG8_STAGE(PG8_SB(1, 0), cB + kstep, voffB); PG8_STAGE(PG8_SA(1, 0), cA + kstep, voffA); if constexpr (!HN) PG8_STAGE(PG8_SB(1, 1), cB + hstep + kstep, voffB);
;     __device__ __forceinline__ void pre(const Unit& un, int wr, int wid, int lane, LAS unsigned char*) const {
;     ...
;         for (int a = 0; a < 2; ++a) {
;             const size_t row = (size_t)(un.pm * 256 + wr * 64 + 128 * a + lane);
;             const f32x4* pa = (const f32x4*)(ssqa + row * 16); const f32x4* ps = (const f32x4*)(ssqs + row * 32);
;             float sa = 0.f, ss = 0.f;
; #pragma unroll
;             for (int i = 0; i < 4; ++i) { const f32x4 t = pa[i]; sa += (t[0] + t[1]) + (t[2] + t[3]); }
; #pragma unroll
;             for (int i = 0; i < 8; ++i) { const f32x4 u = ps[i]; ss += (u[0] + u[1]) + (u[2] + u[3]); }
;             const float ra = rsqrtf(sa * (1.f / 1024.f) + 1e-6f), rs = rsqrtf(ss * (1.f / 1024.f) + 1e-6f);
;             tab[(a * 64 + lane) * 2] = ra / rs; tab[(a * 64 + lane) * 2 + 1] = rs;
;         }
	v_mov_b32_e32 v33, v78
	v_mov_b32_e32 v43, v79
	v_mov_b32_e32 v45, v80
	v_mov_b32_e32 v47, v81
	v_pk_add_f32 v[26:27], v[32:33], v[42:43]
	v_pk_add_f32 v[28:29], v[44:45], v[46:47]
	v_mov_b32_e32 v17, v68
	v_pk_add_f32 v[26:27], v[26:27], v[28:29]
	v_mov_b32_e32 v28, v75
	v_mov_b32_e32 v29, v76
	v_mov_b32_e32 v21, v77
	v_mov_b32_e32 v20, v74
	v_pk_add_f32 v[20:21], v[28:29], v[20:21]
	v_pk_add_f32 v[26:27], v[26:27], v[26:27] op_sel:[0,1] op_sel_hi:[1,0]
	v_pk_add_f32 v[20:21], v[20:21], v[20:21] op_sel:[0,1] op_sel_hi:[1,0]
	v_mov_b32_e32 v27, v66
	v_mov_b32_e32 v21, v67
	v_mov_b32_e32 v19, v69
	v_pk_add_f32 v[12:13], v[26:27], v[20:21]
	v_pk_add_f32 v[14:15], v[16:17], v[18:19]
	s_nop 0
	v_pk_add_f32 v[12:13], v[12:13], v[14:15]
	v_add_f32_e32 v14, 0, v5
	v_mov_b32_e32 v15, v0
	v_pk_add_f32 v[0:1], v[14:15], v[6:7]
	v_mov_b64_e32 v[14:15], s[0:1]
	v_pk_add_f32 v[0:1], v[0:1], v[2:3]
	v_mov_b32_e32 v2, v12
	v_mov_b32_e32 v3, v0
	v_mov_b32_e32 v0, v13
	v_pk_add_f32 v[0:1], v[2:3], v[0:1]
	s_nop 0
	v_pk_fma_f32 v[0:1], v[0:1], s[2:3], v[14:15] op_sel_hi:[1,0,0]
	s_nop 0
	v_mul_f32_e32 v2, 0x4b800000, v1
	v_cmp_gt_f32_e64 s[0:1], s80, v1
	v_cmp_gt_f32_e32 vcc, s80, v0
	s_nop 0
	v_cndmask_b32_e64 v1, v1, v2, s[0:1]
	v_rsq_f32_e32 v1, v1
	s_nop 0
	v_mul_f32_e32 v2, 0x45800000, v1
	v_cndmask_b32_e64 v1, v1, v2, s[0:1]
	v_mul_f32_e32 v2, 0x4b800000, v0
	v_cndmask_b32_e32 v0, v0, v2, vcc
	v_rsq_f32_e32 v0, v0
	s_nop 0
	v_mul_f32_e32 v2, 0x45800000, v0
	v_cndmask_b32_e32 v13, v0, v2, vcc
	v_div_scale_f32 v0, s[0:1], v13, v13, v1
	v_rcp_f32_e32 v2, v0
	s_nop 0
	v_fma_f32 v3, -v0, v2, 1.0
	v_fmac_f32_e32 v2, v3, v2
	v_div_scale_f32 v3, vcc, v1, v13, v1
	v_mul_f32_e32 v5, v3, v2
	v_fma_f32 v6, -v0, v5, v3
	v_fmac_f32_e32 v5, v6, v2
	v_fma_f32 v0, -v0, v5, v3
	v_div_fmas_f32 v0, v0, v2, v5
	v_div_fixup_f32 v12, v0, v13, v1
	v_add_u32_e32 v0, 0x80, v4
	v_ashrrev_i32_e32 v1, 31, v0
	v_lshlrev_b64 v[2:3], 6, v[0:1]
	v_lshl_add_u64 v[16:17], s[34:35], 0, v[2:3]
	v_lshlrev_b64 v[22:23], 7, v[0:1]
	global_load_dwordx4 v[0:3], v[16:17], off offset:48
	global_load_dwordx4 v[4:7], v[16:17], off offset:32
	global_load_dwordx4 v[8:11], v[16:17], off offset:16
	s_nop 0
	global_load_dwordx4 v[16:19], v[16:17], off
	v_lshl_add_u64 v[22:23], s[42:43], 0, v[22:23]
	global_load_dwordx4 v[82:85], v[22:23], off offset:48
	global_load_dwordx4 v[86:89], v[22:23], off offset:32
	global_load_dwordx4 v[90:93], v[22:23], off
	global_load_dwordx4 v[94:97], v[22:23], off offset:16
	global_load_dwordx4 v[98:101], v[22:23], off offset:112
	global_load_dwordx4 v[102:105], v[22:23], off offset:96
	global_load_dwordx4 v[106:109], v[22:23], off offset:80
	global_load_dwordx4 v[110:113], v[22:23], off offset:64
	s_waitcnt vmcnt(0)
	v_mov_b32_e32 v20, v17
	v_mov_b32_e32 v21, v18
	v_mov_b32_e32 v17, v19
	v_pk_add_f32 v[16:17], v[20:21], v[16:17]
	v_add_f32_e32 v18, v4, v5
	v_add_f32_e32 v19, v16, v17
	v_mov_b32_e32 v16, v9
	v_mov_b32_e32 v17, v10
	v_mov_b32_e32 v9, v11
	v_pk_add_f32 v[8:9], v[16:17], v[8:9]
	v_add_f32_e32 v20, v6, v7
	v_pk_add_f32 v[16:17], v[8:9], v[8:9] op_sel:[0,1] op_sel_hi:[1,0]
	v_mov_b32_e32 v21, v3
	s_waitcnt vmcnt(1)
	v_mov_b32_e32 v42, v90
	s_waitcnt vmcnt(0)
	v_mov_b32_e32 v43, v94
	v_mov_b32_e32 v30, v91
	v_mov_b32_e32 v31, v95
	v_pk_add_f32 v[26:27], v[42:43], v[30:31]
	v_mov_b32_e32 v30, v92
	v_mov_b32_e32 v31, v96
	v_mov_b32_e32 v32, v93
	v_mov_b32_e32 v33, v97
	v_pk_add_f32 v[28:29], v[30:31], v[32:33]
	v_add_f32_e32 v30, v84, v85
	v_pk_add_f32 v[26:27], v[26:27], v[28:29]
	v_mov_b32_e32 v28, v87
	v_mov_b32_e32 v29, v88
	v_mov_b32_e32 v9, v89
	v_mov_b32_e32 v8, v86
	v_pk_add_f32 v[8:9], v[28:29], v[8:9]
	v_add_f32_e32 v28, v82, v83
	v_pk_add_f32 v[32:33], v[8:9], v[8:9] op_sel:[0,1] op_sel_hi:[1,0]
	v_add_f32_e32 v17, 0, v26
	v_add_f32_e32 v26, v17, v27
	v_mov_b32_e32 v17, v1
	global_load_lds_dwordx4 v134, s[62:63]
	s_add_i32 m0, s59, 0x12000
	s_waitcnt vmcnt(0)
	v_add_f32_e32 v8, v102, v103
	v_add_f32_e32 v10, v104, v105
	v_mov_b32_e32 v27, v110
	v_mov_b32_e32 v33, v111
	v_mov_b32_e32 v29, v112
	v_mov_b32_e32 v31, v113
	v_pk_add_f32 v[22:23], v[26:27], v[32:33]
	v_pk_add_f32 v[26:27], v[28:29], v[30:31]
	v_mov_b32_e32 v9, v100
	v_pk_add_f32 v[22:23], v[22:23], v[26:27]
	v_mov_b32_e32 v26, v107
	v_mov_b32_e32 v27, v108
	v_mov_b32_e32 v43, v109
	v_mov_b32_e32 v42, v106
	v_pk_add_f32 v[26:27], v[26:27], v[42:43]
	v_pk_add_f32 v[22:23], v[22:23], v[22:23] op_sel:[0,1] op_sel_hi:[1,0]
	v_pk_add_f32 v[26:27], v[26:27], v[26:27] op_sel:[0,1] op_sel_hi:[1,0]
	v_mov_b32_e32 v23, v98
	v_mov_b32_e32 v27, v99
	v_mov_b32_e32 v11, v101
	v_pk_add_f32 v[4:5], v[22:23], v[26:27]
	v_pk_add_f32 v[6:7], v[8:9], v[10:11]
	global_load_lds_dwordx4 v138, s[62:63]
	v_pk_add_f32 v[4:5], v[4:5], v[6:7]
	v_add_f32_e32 v6, 0, v19
	v_mov_b32_e32 v19, v2
	v_mov_b32_e32 v7, v0
	v_pk_add_f32 v[2:3], v[18:19], v[20:21]
	v_pk_add_f32 v[0:1], v[6:7], v[16:17]
	s_nop 0
	v_pk_add_f32 v[0:1], v[0:1], v[2:3]
	v_mov_b32_e32 v2, v4
	v_mov_b32_e32 v3, v0
	v_mov_b32_e32 v0, v5
	v_pk_add_f32 v[0:1], v[2:3], v[0:1]
	s_nop 0
	v_pk_fma_f32 v[0:1], v[0:1], s[2:3], v[14:15] op_sel_hi:[1,0,0]
	s_nop 0
	v_mul_f32_e32 v2, 0x4b800000, v1
	v_cmp_gt_f32_e64 s[0:1], s80, v1
	v_cmp_gt_f32_e32 vcc, s80, v0
	s_nop 0
	v_cndmask_b32_e64 v1, v1, v2, s[0:1]
	v_rsq_f32_e32 v1, v1
	s_nop 0
	v_mul_f32_e32 v2, 0x45800000, v1
	v_cndmask_b32_e64 v2, v1, v2, s[0:1]
	v_mul_f32_e32 v1, 0x4b800000, v0
	v_cndmask_b32_e32 v0, v0, v1, vcc
	v_rsq_f32_e32 v0, v0
	s_nop 0
	v_mul_f32_e32 v1, 0x45800000, v0
	v_cndmask_b32_e32 v1, v0, v1, vcc
	v_div_scale_f32 v0, s[0:1], v1, v1, v2
	s_add_u32 s0, s62, 0x80000
	s_addc_u32 s1, s63, 0
	s_add_i32 m0, s59, 0x14000
	v_rcp_f32_e32 v3, v0
	s_nop 0
	global_load_lds_dwordx4 v134, s[0:1]
	s_add_i32 m0, s59, 0x16000
	v_fma_f32 v4, -v0, v3, 1.0
	global_load_lds_dwordx4 v138, s[0:1]
	s_add_u32 s0, s22, s36
	s_addc_u32 s1, s23, s37
	s_add_i32 s72, s59, 0x2000
	s_mov_b32 m0, s59
	s_add_u32 s36, s0, 0x80000
	global_load_lds_dwordx4 v132, s[0:1]
	s_mov_b32 m0, s72
	s_addc_u32 s37, s1, 0
	s_add_i32 s73, s59, 0x4000
	global_load_lds_dwordx4 v136, s[0:1]
	s_mov_b32 m0, s73
	s_add_i32 s76, s59, 0x6000
	global_load_lds_dwordx4 v132, s[36:37]
	s_mov_b32 m0, s76
	v_fmac_f32_e32 v3, v4, v3
	global_load_lds_dwordx4 v136, s[36:37]
	v_div_scale_f32 v4, vcc, v2, v1, v2
	v_mul_f32_e32 v5, v4, v3
	v_fma_f32 v6, -v0, v5, v4
	v_fmac_f32_e32 v5, v6, v3
	v_fma_f32 v0, -v0, v5, v4
	v_div_fmas_f32 v0, v0, v3, v5
	v_div_fixup_f32 v0, v0, v1, v2
	s_cmp_eq_u32 s38, 1
	ds_write2st64_b64 v148, v[12:13], v[0:1] offset1:1
	v_mov_b32_e32 v44, v108
	v_mov_b32_e32 v45, v109
	v_mov_b32_e32 v46, v110
	v_mov_b32_e32 v47, v111
	v_mov_b32_e32 v48, v112
	v_mov_b32_e32 v49, v113
	v_lshl_add_u64 v[0:1], s[62:63], 0, v[134:135]
	v_lshl_add_u64 v[2:3], s[62:63], 0, v[138:139]
	v_lshl_add_u64 v[4:5], s[0:1], 0, v[132:133]
	v_lshl_add_u64 v[6:7], s[0:1], 0, v[136:137]
	s_cselect_b64 s[44:45], -1, 0
	s_cmp_lg_u32 s38, 1
	s_cbranch_scc1 .LBB0_1153
	s_barrier
